# V^T GEMM epilogue: 16-byte stores (full lines per row) issued write-through (sc1) so the output reaches memory during the epilogue instead of in the barrier's L2 write-back
# speedup vs baseline: 1.0025x; 1.0001x over previous
; #define PG8_STAGE(bufoff, gbase, voff) do { _Pragma("unroll") for (int _i = 0; _i < 2; ++_i) \
;         __builtin_amdgcn_global_load_lds((const unsigned*)((const char*)(gbase) + (voff)[_i]), (PG8_LAS unsigned*)(lds + (bufoff) + ldsw + _i * 8192), 16, 0, 0); } while (0)
; #define PG8_LDA(dst, b, h) do { _Pragma("unroll") for (int m = 0; m < 4; ++m) _Pragma("unroll") for (int k = 0; k < 2; ++k) dst[m][k] = *(const PG8_LAS bf16x8*)(lds + PG8_SA(b, h) + aoff + m * 2048 + k * 1024); } while (0)
; #define PG8_LDB(dst, b, h) do { _Pragma("unroll") for (int n = 0; n < 2; ++n) _Pragma("unroll") for (int k = 0; k < 2; ++k) dst[n][k] = *(const PG8_LAS bf16x8*)(lds + PG8_SB(b, h) + boff + n * 2048 + k * 1024); } while (0)
; #define PG8_MMA(ai, bj, At, Bt) do { __builtin_amdgcn_s_setprio(1); _Pragma("unroll") for (int m = 0; m < 4; ++m) _Pragma("unroll") for (int n = 0; n < 2; ++n) _Pragma("unroll") for (int k = 0; k < 2; ++k) \
;         acc[ai][bj][m][n] = __builtin_amdgcn_mfma_f32_16x16x32_bf16(Bt[n][k], At[m][k], acc[ai][bj][m][n], 0, 0, 0); __builtin_amdgcn_s_setprio(0); } while (0)
; #define PG8_WAIT_V(n) asm volatile("s_waitcnt vmcnt(" #n ")" ::: "memory")
; #define PG8_WAIT_L(n) asm volatile("s_waitcnt lgkmcnt(" #n ")" ::: "memory")
; #define PG8_BAR __builtin_amdgcn_s_barrier()
; #define PG8_SCHED __builtin_amdgcn_sched_barrier(0)
; template <class Epi, class Sched, bool ALIGN_EPI = false, bool SP2 = false>
; __device__ __forceinline__ void gemm_phase(PG8_LAS unsigned char* lds, const Gemm g, const Sched& S, const Epi& E) {
;     ...
;             PG8_LDB(B0, 0, 0); PG8_LDB(B1, 0, 1); PG8_SCHED; PG8_LDA(At, 0, 0); PG8_STAGE(PG8_SA(1, 1), a1 + hstep, voffA);
;             PG8_WAIT_V(8); PG8_WAIT_L(0); PG8_BAR; PG8_MMA(0, 0, At, B0); PG8_MMA(0, 1, At, B1); PG8_BAR; PG8_SCHED;
;             PG8_LDA(At, 0, 1); PG8_STAGE(PG8_SB(0, 0), b2, voffB); PG8_STAGE(PG8_SB(0, 1), b2 + hstep, voffB); PG8_STAGE(PG8_SA(0, 0), a2, voffA);
;             PG8_WAIT_V(8); PG8_WAIT_L(0); PG8_BAR; PG8_MMA(1, 0, At, B0); PG8_MMA(1, 1, At, B1); PG8_BAR; PG8_SCHED;
.LBB0_576:
	ds_read_b128 v[146:149], v167
	ds_read_b128 v[150:153], v167 offset:1024
	ds_read_b128 v[154:157], v167 offset:2048
	ds_read_b128 v[158:161], v167 offset:3072
	ds_read_b128 v[172:175], v168
	ds_read_b128 v[176:179], v168 offset:1024
	ds_read_b128 v[180:183], v168 offset:2048
	ds_read_b128 v[188:191], v168 offset:3072
	s_add_u32 s22, s20, 0xfffc0080
	s_addc_u32 s23, s21, -1
	s_cmp_eq_u32 s70, 12
	s_cselect_b32 s25, s13, s23
	s_cselect_b32 s24, s50, s22
	s_cselect_b32 s23, s11, s69
	s_cselect_b32 s22, s51, s58
	v_lshl_add_u64 v[224:225], s[20:21], 0, v[138:139]
	s_add_i32 m0, s19, 0xc000
	ds_read_b128 v[192:195], v169
	ds_read_b128 v[196:199], v169 offset:1024
	ds_read_b128 v[200:203], v169 offset:2048
	ds_read_b128 v[204:207], v169 offset:3072
	ds_read_b128 v[208:211], v169 offset:4096
	ds_read_b128 v[212:215], v169 offset:5120
	ds_read_b128 v[216:219], v169 offset:6144
	ds_read_b128 v[220:223], v169 offset:7168
	global_load_lds_dwordx4 v[224:225], off
	v_lshl_add_u64 v[224:225], s[20:21], 0, v[140:141]
	s_add_i32 m0, s19, 0xe000
	s_nop 0
	global_load_lds_dwordx4 v[224:225], off
	s_waitcnt vmcnt(8)
	s_waitcnt lgkmcnt(0)
	s_barrier
	s_setprio 1
	s_waitcnt lgkmcnt(0)
	v_mfma_f32_16x16x32_bf16 v[124:127], v[146:149], v[192:195], v[124:127]
	v_mfma_f32_16x16x32_bf16 v[120:123], v[154:157], v[192:195], v[120:123]
	v_mfma_f32_16x16x32_bf16 v[116:119], v[146:149], v[200:203], v[116:119]
	v_mfma_f32_16x16x32_bf16 v[112:115], v[154:157], v[200:203], v[112:115]
	v_mfma_f32_16x16x32_bf16 v[92:95], v[146:149], v[208:211], v[92:95]
	v_mfma_f32_16x16x32_bf16 v[88:91], v[154:157], v[208:211], v[88:91]
	v_mfma_f32_16x16x32_bf16 v[76:79], v[146:149], v[216:219], v[76:79]
	v_mfma_f32_16x16x32_bf16 v[72:75], v[154:157], v[216:219], v[72:75]
	v_mfma_f32_16x16x32_bf16 v[124:127], v[150:153], v[196:199], v[124:127]
	v_mfma_f32_16x16x32_bf16 v[120:123], v[158:161], v[196:199], v[120:123]
	v_mfma_f32_16x16x32_bf16 v[116:119], v[150:153], v[204:207], v[116:119]
	v_mfma_f32_16x16x32_bf16 v[112:115], v[158:161], v[204:207], v[112:115]
	v_mfma_f32_16x16x32_bf16 v[92:95], v[150:153], v[212:215], v[92:95]
	v_mfma_f32_16x16x32_bf16 v[88:91], v[158:161], v[212:215], v[88:91]
	v_mfma_f32_16x16x32_bf16 v[76:79], v[150:153], v[220:223], v[76:79]
	v_mfma_f32_16x16x32_bf16 v[72:75], v[158:161], v[220:223], v[72:75]
	s_setprio 0
	s_setprio 1
	v_mfma_f32_16x16x32_bf16 v[108:111], v[172:175], v[192:195], v[108:111]
	v_mfma_f32_16x16x32_bf16 v[104:107], v[180:183], v[192:195], v[104:107]
	v_mfma_f32_16x16x32_bf16 v[100:103], v[172:175], v[200:203], v[100:103]
	v_mfma_f32_16x16x32_bf16 v[96:99], v[180:183], v[200:203], v[96:99]
	v_mfma_f32_16x16x32_bf16 v[84:87], v[172:175], v[208:211], v[84:87]
	v_mfma_f32_16x16x32_bf16 v[80:83], v[180:183], v[208:211], v[80:83]
	v_mfma_f32_16x16x32_bf16 v[68:71], v[172:175], v[216:219], v[68:71]
	v_mfma_f32_16x16x32_bf16 v[64:67], v[180:183], v[216:219], v[64:67]
	v_mfma_f32_16x16x32_bf16 v[108:111], v[176:179], v[196:199], v[108:111]
	v_mfma_f32_16x16x32_bf16 v[104:107], v[188:191], v[196:199], v[104:107]
	v_mfma_f32_16x16x32_bf16 v[100:103], v[176:179], v[204:207], v[100:103]
	v_mfma_f32_16x16x32_bf16 v[96:99], v[188:191], v[204:207], v[96:99]
	v_mfma_f32_16x16x32_bf16 v[84:87], v[176:179], v[212:215], v[84:87]
	v_mfma_f32_16x16x32_bf16 v[80:83], v[188:191], v[212:215], v[80:83]
	v_mfma_f32_16x16x32_bf16 v[68:71], v[176:179], v[220:223], v[68:71]
	v_mfma_f32_16x16x32_bf16 v[64:67], v[188:191], v[220:223], v[64:67]
	s_setprio 0
	s_barrier
	s_add_i32 s71, s47, s30
	v_lshl_add_u64 v[224:225], s[22:23], 0, v[130:131]
	s_mov_b32 m0, s71
	ds_read_b128 v[192:195], v169 offset:16384
	ds_read_b128 v[196:199], v169 offset:17408
	ds_read_b128 v[200:203], v169 offset:18432
	ds_read_b128 v[204:207], v169 offset:19456
	ds_read_b128 v[208:211], v169 offset:20480
	ds_read_b128 v[212:215], v169 offset:21504
	ds_read_b128 v[216:219], v169 offset:22528
	ds_read_b128 v[220:223], v169 offset:23552
	global_load_lds_dwordx4 v[224:225], off
	s_add_i32 m0, s71, 0x2000
	s_add_u32 s72, s22, 0x40000
	v_lshl_add_u64 v[226:227], s[22:23], 0, v[134:135]
	s_addc_u32 s73, s23, 0
	s_add_i32 s71, s48, s30
	global_load_lds_dwordx4 v[226:227], off
	v_lshl_add_u64 v[228:229], s[72:73], 0, v[130:131]
	s_mov_b32 m0, s71
	v_lshl_add_u64 v[230:231], s[24:25], 0, v[132:133]
	global_load_lds_dwordx4 v[228:229], off
	v_lshl_add_u64 v[228:229], s[72:73], 0, v[134:135]
	s_add_i32 m0, s71, 0x2000
	s_nop 0
	global_load_lds_dwordx4 v[228:229], off
	v_lshl_add_u64 v[228:229], s[24:25], 0, v[128:129]
	s_mov_b32 m0, s19
	s_nop 0
	global_load_lds_dwordx4 v[228:229], off
	s_mov_b32 m0, s31
	s_nop 0
	global_load_lds_dwordx4 v[230:231], off
	s_waitcnt vmcnt(8)
	s_waitcnt lgkmcnt(0)
	s_barrier
; #define PG8_STAGE(bufoff, gbase, voff) do { _Pragma("unroll") for (int _i = 0; _i < 2; ++_i) \
;         __builtin_amdgcn_global_load_lds((const unsigned*)((const char*)(gbase) + (voff)[_i]), (PG8_LAS unsigned*)(lds + (bufoff) + ldsw + _i * 8192), 16, 0, 0); } while (0)
; #define PG8_LDA(dst, b, h) do { _Pragma("unroll") for (int m = 0; m < 4; ++m) _Pragma("unroll") for (int k = 0; k < 2; ++k) dst[m][k] = *(const PG8_LAS bf16x8*)(lds + PG8_SA(b, h) + aoff + m * 2048 + k * 1024); } while (0)
; #define PG8_LDB(dst, b, h) do { _Pragma("unroll") for (int n = 0; n < 2; ++n) _Pragma("unroll") for (int k = 0; k < 2; ++k) dst[n][k] = *(const PG8_LAS bf16x8*)(lds + PG8_SB(b, h) + boff + n * 2048 + k * 1024); } while (0)
; #define PG8_MMA(ai, bj, At, Bt) do { __builtin_amdgcn_s_setprio(1); _Pragma("unroll") for (int m = 0; m < 4; ++m) _Pragma("unroll") for (int n = 0; n < 2; ++n) _Pragma("unroll") for (int k = 0; k < 2; ++k) \
;         acc[ai][bj][m][n] = __builtin_amdgcn_mfma_f32_16x16x32_bf16(Bt[n][k], At[m][k], acc[ai][bj][m][n], 0, 0, 0); __builtin_amdgcn_s_setprio(0); } while (0)
; #define PG8_WAIT_V(n) asm volatile("s_waitcnt vmcnt(" #n ")" ::: "memory")
; #define PG8_WAIT_L(n) asm volatile("s_waitcnt lgkmcnt(" #n ")" ::: "memory")
; #define PG8_BAR __builtin_amdgcn_s_barrier()
; #define PG8_SCHED __builtin_amdgcn_sched_barrier(0)
; template <class Epi, class Sched, bool ALIGN_EPI = false, bool SP2 = false>
; __device__ __forceinline__ void gemm_phase(PG8_LAS unsigned char* lds, const Gemm g, const Sched& S, const Epi& E) {
;     ...
;             PG8_WAIT_V(8); PG8_WAIT_L(0); PG8_BAR; PG8_MMA(1, 0, At, B0); PG8_MMA(1, 1, At, B1); PG8_BAR; PG8_SCHED;
;             PG8_LDB(B0, 1, 0); PG8_LDB(B1, 1, 1); PG8_SCHED; PG8_LDA(At, 1, 0); PG8_STAGE(PG8_SA(0, 1), a2 + hstep, voffA);
;             PG8_WAIT_V(8); PG8_WAIT_L(0); PG8_BAR; PG8_MMA(0, 0, At, B0); PG8_MMA(0, 1, At, B1); PG8_BAR; PG8_SCHED;
	s_setprio 1
	s_waitcnt lgkmcnt(0)
	v_mfma_f32_16x16x32_bf16 v[60:63], v[146:149], v[192:195], v[60:63]
	v_mfma_f32_16x16x32_bf16 v[56:59], v[154:157], v[192:195], v[56:59]
	v_mfma_f32_16x16x32_bf16 v[44:47], v[146:149], v[200:203], v[44:47]
	v_mfma_f32_16x16x32_bf16 v[40:43], v[154:157], v[200:203], v[40:43]
	v_mfma_f32_16x16x32_bf16 v[28:31], v[146:149], v[208:211], v[28:31]
	v_mfma_f32_16x16x32_bf16 v[24:27], v[154:157], v[208:211], v[24:27]
	v_mfma_f32_16x16x32_bf16 v[12:15], v[146:149], v[216:219], v[12:15]
	v_mfma_f32_16x16x32_bf16 v[8:11], v[154:157], v[216:219], v[8:11]
	v_mfma_f32_16x16x32_bf16 v[60:63], v[150:153], v[196:199], v[60:63]
	v_mfma_f32_16x16x32_bf16 v[56:59], v[158:161], v[196:199], v[56:59]
	v_mfma_f32_16x16x32_bf16 v[44:47], v[150:153], v[204:207], v[44:47]
	v_mfma_f32_16x16x32_bf16 v[40:43], v[158:161], v[204:207], v[40:43]
	v_mfma_f32_16x16x32_bf16 v[28:31], v[150:153], v[212:215], v[28:31]
	v_mfma_f32_16x16x32_bf16 v[24:27], v[158:161], v[212:215], v[24:27]
	v_mfma_f32_16x16x32_bf16 v[12:15], v[150:153], v[220:223], v[12:15]
	v_mfma_f32_16x16x32_bf16 v[8:11], v[158:161], v[220:223], v[8:11]
	s_setprio 0
	s_setprio 1
	v_mfma_f32_16x16x32_bf16 v[52:55], v[172:175], v[192:195], v[52:55]
	v_mfma_f32_16x16x32_bf16 v[48:51], v[180:183], v[192:195], v[48:51]
	v_mfma_f32_16x16x32_bf16 v[36:39], v[172:175], v[200:203], v[36:39]
	v_mfma_f32_16x16x32_bf16 v[32:35], v[180:183], v[200:203], v[32:35]
	v_mfma_f32_16x16x32_bf16 v[20:23], v[172:175], v[208:211], v[20:23]
	v_mfma_f32_16x16x32_bf16 v[16:19], v[180:183], v[208:211], v[16:19]
	v_mfma_f32_16x16x32_bf16 v[4:7], v[172:175], v[216:219], v[4:7]
	v_mfma_f32_16x16x32_bf16 v[0:3], v[180:183], v[216:219], v[0:3]
	v_mfma_f32_16x16x32_bf16 v[52:55], v[176:179], v[196:199], v[52:55]
	v_mfma_f32_16x16x32_bf16 v[48:51], v[188:191], v[196:199], v[48:51]
	v_mfma_f32_16x16x32_bf16 v[36:39], v[176:179], v[204:207], v[36:39]
	v_mfma_f32_16x16x32_bf16 v[32:35], v[188:191], v[204:207], v[32:35]
	v_mfma_f32_16x16x32_bf16 v[20:23], v[176:179], v[212:215], v[20:23]
	v_mfma_f32_16x16x32_bf16 v[16:19], v[188:191], v[212:215], v[16:19]
	v_mfma_f32_16x16x32_bf16 v[4:7], v[176:179], v[220:223], v[4:7]
	v_mfma_f32_16x16x32_bf16 v[0:3], v[188:191], v[220:223], v[0:3]
	s_setprio 0
	s_barrier
	s_add_i32 s71, 0, 0x18000
	s_add_i32 s72, 0, 0x1c000
	v_add_u32_e32 v158, s71, v164
	v_add_u32_e32 v171, s72, v164
	ds_read_b128 v[146:149], v158
	ds_read_b128 v[150:153], v158 offset:1024
	ds_read_b128 v[154:157], v158 offset:2048
	ds_read_b128 v[158:161], v158 offset:3072
	ds_read_b128 v[172:175], v171
	ds_read_b128 v[176:179], v171 offset:1024
	ds_read_b128 v[180:183], v171 offset:2048
	ds_read_b128 v[188:191], v171 offset:3072
	s_add_u32 s24, s24, 0x40000
	s_addc_u32 s25, s25, 0
	s_mov_b32 m0, s36
	v_lshl_add_u64 v[234:235], s[24:25], 0, v[128:129]
	ds_read_b128 v[192:195], v169 offset:32768
	ds_read_b128 v[196:199], v169 offset:33792
	ds_read_b128 v[200:203], v169 offset:34816
	ds_read_b128 v[204:207], v169 offset:35840
	ds_read_b128 v[208:211], v169 offset:36864
	ds_read_b128 v[212:215], v169 offset:37888
	ds_read_b128 v[216:219], v169 offset:38912
	ds_read_b128 v[220:223], v169 offset:39936
	global_load_lds_dwordx4 v[234:235], off
	v_lshl_add_u64 v[234:235], s[24:25], 0, v[132:133]
	s_mov_b32 m0, s37
	s_nop 0
	global_load_lds_dwordx4 v[234:235], off
	s_waitcnt vmcnt(8)
	s_waitcnt lgkmcnt(0)
	s_barrier
	s_setprio 1
	s_waitcnt lgkmcnt(0)
	v_mfma_f32_16x16x32_bf16 v[124:127], v[146:149], v[192:195], v[124:127]
	v_mfma_f32_16x16x32_bf16 v[120:123], v[154:157], v[192:195], v[120:123]
	v_mfma_f32_16x16x32_bf16 v[116:119], v[146:149], v[200:203], v[116:119]
	v_mfma_f32_16x16x32_bf16 v[112:115], v[154:157], v[200:203], v[112:115]
	v_mfma_f32_16x16x32_bf16 v[92:95], v[146:149], v[208:211], v[92:95]
	v_mfma_f32_16x16x32_bf16 v[88:91], v[154:157], v[208:211], v[88:91]
	v_mfma_f32_16x16x32_bf16 v[76:79], v[146:149], v[216:219], v[76:79]
	v_mfma_f32_16x16x32_bf16 v[72:75], v[154:157], v[216:219], v[72:75]
	v_mfma_f32_16x16x32_bf16 v[124:127], v[150:153], v[196:199], v[124:127]
	v_mfma_f32_16x16x32_bf16 v[120:123], v[158:161], v[196:199], v[120:123]
	v_mfma_f32_16x16x32_bf16 v[116:119], v[150:153], v[204:207], v[116:119]
	v_mfma_f32_16x16x32_bf16 v[112:115], v[158:161], v[204:207], v[112:115]
	v_mfma_f32_16x16x32_bf16 v[92:95], v[150:153], v[212:215], v[92:95]
	v_mfma_f32_16x16x32_bf16 v[88:91], v[158:161], v[212:215], v[88:91]
	v_mfma_f32_16x16x32_bf16 v[76:79], v[150:153], v[220:223], v[76:79]
	v_mfma_f32_16x16x32_bf16 v[72:75], v[158:161], v[220:223], v[72:75]
	s_setprio 0
	s_setprio 1
	v_mfma_f32_16x16x32_bf16 v[108:111], v[172:175], v[192:195], v[108:111]
	v_mfma_f32_16x16x32_bf16 v[104:107], v[180:183], v[192:195], v[104:107]
	v_mfma_f32_16x16x32_bf16 v[100:103], v[172:175], v[200:203], v[100:103]
	v_mfma_f32_16x16x32_bf16 v[96:99], v[180:183], v[200:203], v[96:99]
	v_mfma_f32_16x16x32_bf16 v[84:87], v[172:175], v[208:211], v[84:87]
	v_mfma_f32_16x16x32_bf16 v[80:83], v[180:183], v[208:211], v[80:83]
	v_mfma_f32_16x16x32_bf16 v[68:71], v[172:175], v[216:219], v[68:71]
	v_mfma_f32_16x16x32_bf16 v[64:67], v[180:183], v[216:219], v[64:67]
	v_mfma_f32_16x16x32_bf16 v[108:111], v[176:179], v[196:199], v[108:111]
	v_mfma_f32_16x16x32_bf16 v[104:107], v[188:191], v[196:199], v[104:107]
	v_mfma_f32_16x16x32_bf16 v[100:103], v[176:179], v[204:207], v[100:103]
	v_mfma_f32_16x16x32_bf16 v[96:99], v[188:191], v[204:207], v[96:99]
	v_mfma_f32_16x16x32_bf16 v[84:87], v[176:179], v[212:215], v[84:87]
	v_mfma_f32_16x16x32_bf16 v[80:83], v[188:191], v[212:215], v[80:83]
	v_mfma_f32_16x16x32_bf16 v[68:71], v[176:179], v[220:223], v[68:71]
	v_mfma_f32_16x16x32_bf16 v[64:67], v[188:191], v[220:223], v[64:67]
	s_setprio 0
	s_barrier
; #define PG8_STAGE(bufoff, gbase, voff) do { _Pragma("unroll") for (int _i = 0; _i < 2; ++_i) \
;         __builtin_amdgcn_global_load_lds((const unsigned*)((const char*)(gbase) + (voff)[_i]), (PG8_LAS unsigned*)(lds + (bufoff) + ldsw + _i * 8192), 16, 0, 0); } while (0)
; #define PG8_LDA(dst, b, h) do { _Pragma("unroll") for (int m = 0; m < 4; ++m) _Pragma("unroll") for (int k = 0; k < 2; ++k) dst[m][k] = *(const PG8_LAS bf16x8*)(lds + PG8_SA(b, h) + aoff + m * 2048 + k * 1024); } while (0)
; #define PG8_WAIT_V(n) asm volatile("s_waitcnt vmcnt(" #n ")" ::: "memory")
; #define PG8_WAIT_L(n) asm volatile("s_waitcnt lgkmcnt(" #n ")" ::: "memory")
; #define PG8_BAR __builtin_amdgcn_s_barrier()
;     __device__ __forceinline__ void operator()(const f32x4 (&acc)[2][2][4][2], const Unit& u, int wr, int wc, int fr, int fq) const {
;         const int row0 = u.pm * BM + wr * 64 + fr, col0 = u.pn * BM + wc * 32 + 8 * fq;
;         f32x4 cs[2][2];
; #pragma unroll
;         for (int bj = 0; bj < 2; ++bj)
; #pragma unroll
;             for (int n = 0; n < 2; ++n) { const f32x4 q = *(const f32x4*)(ssq + col0 + bj * HALF + 4 * n);
; #pragma unroll
;                 for (int e = 0; e < 4; ++e) cs[bj][n][e] = __builtin_amdgcn_rsqf(q[e] * (1.0f / 1024.0f) + 1e-6f); }
; #pragma unroll
;         for (int ai = 0; ai < 2; ++ai)
; #pragma unroll
;             for (int m = 0; m < 4; ++m) { const int row = row0 + ai * HALF + m * 16, h = row >> 6, d = row & 63, dt = d >> 5, r = d & 31;
; #pragma unroll
;                 for (int bj = 0; bj < 2; ++bj) { const int col = col0 + bj * HALF, b = col >> 12, tl = col & 4095, kt = tl >> 5, k0 = tl & 31, s = k0 >> 4, half = (k0 >> 3) & 1, bh = b * 16 + h;
;                     const f32x4 v0 = acc[ai][bj][m][0] * cs[bj][0], v1 = acc[ai][bj][m][1] * cs[bj][1];
;                     bf16_t* p = VF + (((size_t)((((bh * 128 + kt) * 2 + dt) * 2 + s) * 64 + r)) << 3) + 4 * half;
; template <class Epi, class Sched, bool ALIGN_EPI = false, bool SP2 = false>
; __device__ __forceinline__ void gemm_phase(PG8_LAS unsigned char* lds, const Gemm g, const Sched& S, const Epi& E) {
;     ...
;             PG8_LDA(At, 1, 1); PG8_STAGE(PG8_SB(1, 0), b3, voffB); PG8_STAGE(PG8_SB(1, 1), b3 + hstep, voffB); PG8_STAGE(PG8_SA(1, 0), a3, voffA);
;             PG8_WAIT_V(8); PG8_WAIT_L(0); PG8_BAR; PG8_MMA(1, 0, At, B0); PG8_MMA(1, 1, At, B1); PG8_BAR; PG8_SCHED;
	s_add_i32 s24, s71, s30
	v_lshl_add_u64 v[224:225], v[224:225], 0, s[4:5]
	s_mov_b32 m0, s24
	ds_read_b128 v[192:195], v169 offset:49152
	ds_read_b128 v[196:199], v169 offset:50176
	ds_read_b128 v[200:203], v169 offset:51200
	ds_read_b128 v[204:207], v169 offset:52224
	ds_read_b128 v[208:211], v169 offset:53248
	ds_read_b128 v[212:215], v169 offset:54272
	ds_read_b128 v[216:219], v169 offset:55296
	ds_read_b128 v[220:223], v169 offset:56320
	global_load_lds_dwordx4 v[224:225], off
	s_add_i32 m0, s24, 0x2000
	s_add_u32 s22, s22, 0x40080
	v_lshl_add_u64 v[224:225], v[226:227], 0, s[4:5]
	s_addc_u32 s23, s23, 0
	s_add_i32 s24, s72, s30
	global_load_lds_dwordx4 v[224:225], off
	v_lshl_add_u64 v[224:225], s[22:23], 0, v[130:131]
	s_mov_b32 m0, s24
	s_nop 0
	global_load_lds_dwordx4 v[224:225], off
	v_lshl_add_u64 v[224:225], s[22:23], 0, v[134:135]
	s_add_i32 m0, s24, 0x2000
	s_nop 0
	global_load_lds_dwordx4 v[224:225], off
	v_lshl_add_u64 v[224:225], v[228:229], 0, s[4:5]
	s_mov_b32 m0, s43
	s_nop 0
	global_load_lds_dwordx4 v[224:225], off
	v_lshl_add_u64 v[224:225], v[230:231], 0, s[4:5]
	s_mov_b32 m0, s44
	s_nop 0
	global_load_lds_dwordx4 v[224:225], off
	s_waitcnt vmcnt(8)
	s_waitcnt lgkmcnt(0)
	s_barrier
	s_setprio 1
	s_waitcnt lgkmcnt(0)
	v_mfma_f32_16x16x32_bf16 v[60:63], v[146:149], v[192:195], v[60:63]
	v_mfma_f32_16x16x32_bf16 v[56:59], v[154:157], v[192:195], v[56:59]
	v_mfma_f32_16x16x32_bf16 v[44:47], v[146:149], v[200:203], v[44:47]
	v_mfma_f32_16x16x32_bf16 v[40:43], v[154:157], v[200:203], v[40:43]
	v_mfma_f32_16x16x32_bf16 v[28:31], v[146:149], v[208:211], v[28:31]
	v_mfma_f32_16x16x32_bf16 v[24:27], v[154:157], v[208:211], v[24:27]
	v_mfma_f32_16x16x32_bf16 v[12:15], v[146:149], v[216:219], v[12:15]
	v_mfma_f32_16x16x32_bf16 v[8:11], v[154:157], v[216:219], v[8:11]
	v_mfma_f32_16x16x32_bf16 v[60:63], v[150:153], v[196:199], v[60:63]
	v_mfma_f32_16x16x32_bf16 v[56:59], v[158:161], v[196:199], v[56:59]
	v_mfma_f32_16x16x32_bf16 v[44:47], v[150:153], v[204:207], v[44:47]
	v_mfma_f32_16x16x32_bf16 v[40:43], v[158:161], v[204:207], v[40:43]
	v_mfma_f32_16x16x32_bf16 v[28:31], v[150:153], v[212:215], v[28:31]
	v_mfma_f32_16x16x32_bf16 v[24:27], v[158:161], v[212:215], v[24:27]
	v_mfma_f32_16x16x32_bf16 v[12:15], v[150:153], v[220:223], v[12:15]
	v_mfma_f32_16x16x32_bf16 v[8:11], v[158:161], v[220:223], v[8:11]
	s_setprio 0
	s_setprio 1
	v_mfma_f32_16x16x32_bf16 v[52:55], v[172:175], v[192:195], v[52:55]
	v_mfma_f32_16x16x32_bf16 v[48:51], v[180:183], v[192:195], v[48:51]
	v_mfma_f32_16x16x32_bf16 v[36:39], v[172:175], v[200:203], v[36:39]
	v_mfma_f32_16x16x32_bf16 v[32:35], v[180:183], v[200:203], v[32:35]
	v_mfma_f32_16x16x32_bf16 v[20:23], v[172:175], v[208:211], v[20:23]
	v_mfma_f32_16x16x32_bf16 v[16:19], v[180:183], v[208:211], v[16:19]
	v_mfma_f32_16x16x32_bf16 v[4:7], v[172:175], v[216:219], v[4:7]
	v_mfma_f32_16x16x32_bf16 v[0:3], v[180:183], v[216:219], v[0:3]
	v_mfma_f32_16x16x32_bf16 v[52:55], v[176:179], v[196:199], v[52:55]
	v_mfma_f32_16x16x32_bf16 v[48:51], v[188:191], v[196:199], v[48:51]
	v_mfma_f32_16x16x32_bf16 v[36:39], v[176:179], v[204:207], v[36:39]
	v_mfma_f32_16x16x32_bf16 v[32:35], v[188:191], v[204:207], v[32:35]
	v_mfma_f32_16x16x32_bf16 v[20:23], v[176:179], v[212:215], v[20:23]
	v_mfma_f32_16x16x32_bf16 v[16:19], v[188:191], v[212:215], v[16:19]
	v_mfma_f32_16x16x32_bf16 v[4:7], v[176:179], v[220:223], v[4:7]
	v_mfma_f32_16x16x32_bf16 v[0:3], v[188:191], v[220:223], v[0:3]
	s_setprio 0
	s_barrier
	s_add_i32 s70, s70, 2
	s_add_u32 s20, s20, 0x100
	s_addc_u32 s21, s21, 0
	s_add_u32 s58, s58, 0x100
	s_addc_u32 s69, s69, 0
	s_cmp_gt_u32 s70, 13
	s_cbranch_scc0 .LBB0_576
	s_lshl_b32 s11, s49, 8
	s_or_b32 s11, s11, s42
	v_or_b32_e32 v146, s11, v163
	v_ashrrev_i32_e32 v147, 31, v146
	v_lshl_add_u64 v[158:159], v[146:147], 2, s[8:9]
	global_load_dwordx4 v[146:149], v[158:159], off
	global_load_dwordx4 v[150:153], v[158:159], off offset:16
	global_load_dwordx4 v[154:157], v[158:159], off offset:512
	s_nop 0
	global_load_dwordx4 v[158:161], v[158:159], off offset:528
	s_lshl_b32 s20, s18, 8
	s_add_i32 s20, s20, s39
	s_and_b32 s18, s49, 0x7ffff0
	s_lshr_b32 s13, s20, 6
	s_lshr_b32 s11, s11, 3
	s_add_i32 s13, s13, s18
	s_and_b32 s11, s11, 0x1ec
	v_lshl_or_b32 v171, s13, 9, v165
	s_or_b32 s13, s11, 16
	v_or_b32_e32 v172, s11, v171
	v_or_b32_e32 v173, s13, v171
	v_lshlrev_b32_e32 v175, 6, v172
	v_lshlrev_b32_e32 v173, 6, v173
	v_or_b32_e32 v172, v175, v162
	v_or_b32_e32 v174, v173, v162
	v_or_b32_e32 v176, v175, v166
	v_or_b32_e32 v178, v173, v166
	v_ashrrev_i32_e32 v173, 31, v172
	v_ashrrev_i32_e32 v175, 31, v174
	v_lshl_add_u64 v[172:173], v[172:173], 4, v[136:137]
	v_lshl_add_u64 v[174:175], v[174:175], 4, v[136:137]
	v_ashrrev_i32_e32 v177, 31, v176
	v_lshl_add_u64 v[176:177], v[176:177], 4, v[136:137]
	s_addk_i32 s20, 0x80
	s_lshr_b32 s20, s20, 6
	s_add_i32 s20, s20, s18
	s_and_b64 vcc, exec, s[2:3]
	s_mov_b32 s49, s10
	s_mov_b32 s18, s12
	s_mov_b64 s[22:23], s[16:17]
	s_waitcnt vmcnt(0)
; __device__ __forceinline__ unsigned cvt_pk_bf16(float lo, float hi) { unsigned r; asm volatile("v_cvt_pk_bf16_f32 %0, %1, %2" : "=v"(r) : "v"(lo), "v"(hi)); return r; }
;     __device__ __forceinline__ void operator()(const f32x4 (&acc)[2][2][4][2], const Unit& u, int wr, int wc, int fr, int fq) const {
;     ...
;             for (int n = 0; n < 2; ++n) { const f32x4 q = *(const f32x4*)(ssq + col0 + bj * HALF + 4 * n);
; #pragma unroll
;                 for (int e = 0; e < 4; ++e) cs[bj][n][e] = __builtin_amdgcn_rsqf(q[e] * (1.0f / 1024.0f) + 1e-6f); }
; #pragma unroll
;         for (int ai = 0; ai < 2; ++ai)
; #pragma unroll
;             for (int m = 0; m < 4; ++m) { const int row = row0 + ai * HALF + m * 16, h = row >> 6, d = row & 63, dt = d >> 5, r = d & 31;
; #pragma unroll
;                 for (int bj = 0; bj < 2; ++bj) { const int col = col0 + bj * HALF, b = col >> 12, tl = col & 4095, kt = tl >> 5, k0 = tl & 31, s = k0 >> 4, half = (k0 >> 3) & 1, bh = b * 16 + h;
;                     const f32x4 v0 = acc[ai][bj][m][0] * cs[bj][0], v1 = acc[ai][bj][m][1] * cs[bj][1];
;                     bf16_t* p = VF + (((size_t)((((bh * 128 + kt) * 2 + dt) * 2 + s) * 64 + r)) << 3) + 4 * half;
;                     *(unsigned long long*)p = (unsigned long long)cvt_pk_bf16(v0[0], v0[1]) | ((unsigned long long)cvt_pk_bf16(v0[2], v0[3]) << 32);
;                     *(unsigned long long*)(p + 256) = (unsigned long long)cvt_pk_bf16(v1[0], v1[1]) | ((unsigned long long)cvt_pk_bf16(v1[2], v1[3]) << 32); }
	v_fmamk_f32 v146, v146, 0x3a800000, v170
	v_fmamk_f32 v147, v147, 0x3a800000, v170
	v_fmamk_f32 v148, v148, 0x3a800000, v170
	v_fmamk_f32 v149, v149, 0x3a800000, v170
	v_fmamk_f32 v150, v150, 0x3a800000, v170
	v_fmamk_f32 v151, v151, 0x3a800000, v170
	v_fmamk_f32 v179, v154, 0x3a800000, v170
	v_fmamk_f32 v180, v155, 0x3a800000, v170
	v_fmamk_f32 v183, v158, 0x3a800000, v170
	v_fmamk_f32 v185, v159, 0x3a800000, v170
	v_fmamk_f32 v152, v152, 0x3a800000, v170
	v_fmamk_f32 v153, v153, 0x3a800000, v170
	v_fmamk_f32 v181, v156, 0x3a800000, v170
	v_fmamk_f32 v182, v157, 0x3a800000, v170
	v_fmamk_f32 v187, v160, 0x3a800000, v170
	v_fmamk_f32 v188, v161, 0x3a800000, v170
	v_rsq_f32_e32 v156, v146
	v_rsq_f32_e32 v157, v147
	v_rsq_f32_e32 v160, v148
	v_rsq_f32_e32 v161, v149
	v_rsq_f32_e32 v154, v150
	v_rsq_f32_e32 v155, v151
	v_rsq_f32_e32 v148, v179
	v_rsq_f32_e32 v149, v180
	v_rsq_f32_e32 v146, v183
	v_rsq_f32_e32 v147, v185
	v_rsq_f32_e32 v158, v152
	v_rsq_f32_e32 v159, v153
	v_rsq_f32_e32 v152, v181
	v_rsq_f32_e32 v153, v182
	v_rsq_f32_e32 v150, v187
	v_rsq_f32_e32 v151, v188
	v_pk_mul_f32 v[124:125], v[124:125], v[156:157]
	v_pk_mul_f32 v[120:121], v[120:121], v[154:155]
	v_pk_mul_f32 v[108:109], v[108:109], v[148:149]
	v_pk_mul_f32 v[104:105], v[104:105], v[146:147]
	v_pk_mul_f32 v[126:127], v[126:127], v[160:161]
	v_pk_mul_f32 v[122:123], v[122:123], v[158:159]
	v_pk_mul_f32 v[110:111], v[110:111], v[152:153]
	v_pk_mul_f32 v[106:107], v[106:107], v[150:151]
	v_cvt_pk_bf16_f32 v188, v124, v125
	v_cvt_pk_bf16_f32 v189, v126, v127
	v_cvt_pk_bf16_f32 v190, v120, v121
	v_cvt_pk_bf16_f32 v191, v122, v123
	s_nop 1
	v_permlane16_swap_b32_e32 v188, v190
	v_permlane16_swap_b32_e32 v189, v191
	global_store_dwordx4 v[172:173], v[188:191], off sc1
	v_cvt_pk_bf16_f32 v192, v108, v109
	v_cvt_pk_bf16_f32 v193, v110, v111
	v_cvt_pk_bf16_f32 v194, v104, v105
	v_cvt_pk_bf16_f32 v195, v106, v107
	s_nop 1
	v_permlane16_swap_b32_e32 v192, v194
	v_permlane16_swap_b32_e32 v193, v195
	global_store_dwordx4 v[174:175], v[192:195], off sc1
	v_pk_mul_f32 v[118:119], v[118:119], v[160:161]
	v_pk_mul_f32 v[116:117], v[116:117], v[156:157]
	v_pk_mul_f32 v[114:115], v[114:115], v[158:159]
	v_cvt_pk_bf16_f32 v196, v116, v117
	v_cvt_pk_bf16_f32 v197, v118, v119
	v_pk_mul_f32 v[112:113], v[112:113], v[154:155]
	v_cvt_pk_bf16_f32 v198, v112, v113
	v_cvt_pk_bf16_f32 v199, v114, v115
	v_ashrrev_i32_e32 v179, 31, v178
	v_pk_mul_f32 v[100:101], v[100:101], v[148:149]
	v_pk_mul_f32 v[98:99], v[98:99], v[150:151]
	v_pk_mul_f32 v[96:97], v[96:97], v[146:147]
	s_nop 1
	v_permlane16_swap_b32_e32 v196, v198
	v_permlane16_swap_b32_e32 v197, v199
	global_store_dwordx4 v[176:177], v[196:199], off sc1
	v_lshl_add_u64 v[104:105], v[178:179], 4, v[136:137]
	v_pk_mul_f32 v[102:103], v[102:103], v[152:153]
	v_cvt_pk_bf16_f32 v200, v100, v101
	v_pk_mul_f32 v[92:93], v[92:93], v[156:157]
	v_cvt_pk_bf16_f32 v201, v102, v103
	v_cvt_pk_bf16_f32 v202, v96, v97
	v_cvt_pk_bf16_f32 v203, v98, v99
	v_or_b32_e32 v98, 2, v171
	s_nop 1
	v_permlane16_swap_b32_e32 v200, v202
	v_permlane16_swap_b32_e32 v201, v203
	global_store_dwordx4 v[104:105], v[200:203], off sc1
	v_or_b32_e32 v96, s11, v98
	v_lshlrev_b32_e32 v99, 6, v96
	v_or_b32_e32 v96, v99, v162
	v_ashrrev_i32_e32 v97, 31, v96
	v_pk_mul_f32 v[88:89], v[88:89], v[154:155]
	v_lshl_add_u64 v[96:97], v[96:97], 4, v[136:137]
	v_pk_mul_f32 v[94:95], v[94:95], v[160:161]
	v_cvt_pk_bf16_f32 v188, v92, v93
	v_pk_mul_f32 v[90:91], v[90:91], v[158:159]
	v_cvt_pk_bf16_f32 v189, v94, v95
	v_cvt_pk_bf16_f32 v190, v88, v89
	v_cvt_pk_bf16_f32 v191, v90, v91
	s_nop 1
	v_permlane16_swap_b32_e32 v188, v190
	v_permlane16_swap_b32_e32 v189, v191
	global_store_dwordx4 v[96:97], v[188:191], off sc1
	v_or_b32_e32 v88, s13, v98
	v_lshlrev_b32_e32 v90, 6, v88
	v_or_b32_e32 v88, v90, v162
	v_ashrrev_i32_e32 v89, 31, v88
	v_pk_mul_f32 v[84:85], v[84:85], v[148:149]
	v_pk_mul_f32 v[80:81], v[80:81], v[146:147]
	v_lshl_add_u64 v[88:89], v[88:89], 4, v[136:137]
	v_pk_mul_f32 v[86:87], v[86:87], v[152:153]
	v_cvt_pk_bf16_f32 v192, v84, v85
	v_pk_mul_f32 v[82:83], v[82:83], v[150:151]
	v_cvt_pk_bf16_f32 v193, v86, v87
	v_cvt_pk_bf16_f32 v194, v80, v81
	v_cvt_pk_bf16_f32 v195, v82, v83
	s_nop 1
	v_permlane16_swap_b32_e32 v192, v194
	v_permlane16_swap_b32_e32 v193, v195
	global_store_dwordx4 v[88:89], v[192:195], off sc1
	v_or_b32_e32 v80, v99, v166
	v_ashrrev_i32_e32 v81, 31, v80
	v_pk_mul_f32 v[76:77], v[76:77], v[156:157]
	v_pk_mul_f32 v[72:73], v[72:73], v[154:155]
	v_lshl_add_u64 v[80:81], v[80:81], 4, v[136:137]
	v_pk_mul_f32 v[78:79], v[78:79], v[160:161]
	v_cvt_pk_bf16_f32 v196, v76, v77
	v_pk_mul_f32 v[74:75], v[74:75], v[158:159]
	v_cvt_pk_bf16_f32 v197, v78, v79
	v_cvt_pk_bf16_f32 v198, v72, v73
	v_cvt_pk_bf16_f32 v199, v74, v75
	s_nop 1
	v_permlane16_swap_b32_e32 v196, v198
	v_permlane16_swap_b32_e32 v197, v199
	global_store_dwordx4 v[80:81], v[196:199], off sc1
	v_or_b32_e32 v72, v90, v166
	v_ashrrev_i32_e32 v73, 31, v72
	v_pk_mul_f32 v[68:69], v[68:69], v[148:149]
	v_pk_mul_f32 v[66:67], v[66:67], v[150:151]
	v_pk_mul_f32 v[64:65], v[64:65], v[146:147]
	v_lshl_add_u64 v[72:73], v[72:73], 4, v[136:137]
	v_pk_mul_f32 v[70:71], v[70:71], v[152:153]
; __device__ __forceinline__ unsigned cvt_pk_bf16(float lo, float hi) { unsigned r; asm volatile("v_cvt_pk_bf16_f32 %0, %1, %2" : "=v"(r) : "v"(lo), "v"(hi)); return r; }
;     __device__ __forceinline__ void operator()(const f32x4 (&acc)[2][2][4][2], const Unit& u, int wr, int wc, int fr, int fq) const {
;     ...
;             for (int m = 0; m < 4; ++m) { const int row = row0 + ai * HALF + m * 16, h = row >> 6, d = row & 63, dt = d >> 5, r = d & 31;
; #pragma unroll
;                 for (int bj = 0; bj < 2; ++bj) { const int col = col0 + bj * HALF, b = col >> 12, tl = col & 4095, kt = tl >> 5, k0 = tl & 31, s = k0 >> 4, half = (k0 >> 3) & 1, bh = b * 16 + h;
;                     const f32x4 v0 = acc[ai][bj][m][0] * cs[bj][0], v1 = acc[ai][bj][m][1] * cs[bj][1];
;                     bf16_t* p = VF + (((size_t)((((bh * 128 + kt) * 2 + dt) * 2 + s) * 64 + r)) << 3) + 4 * half;
;                     *(unsigned long long*)p = (unsigned long long)cvt_pk_bf16(v0[0], v0[1]) | ((unsigned long long)cvt_pk_bf16(v0[2], v0[3]) << 32);
;                     *(unsigned long long*)(p + 256) = (unsigned long long)cvt_pk_bf16(v1[0], v1[1]) | ((unsigned long long)cvt_pk_bf16(v1[2], v1[3]) << 32); }
;                 asm volatile("" ::: "memory"); }
	v_cvt_pk_bf16_f32 v200, v68, v69
	v_pk_mul_f32 v[60:61], v[60:61], v[156:157]
	v_cvt_pk_bf16_f32 v201, v70, v71
	v_cvt_pk_bf16_f32 v202, v64, v65
	v_cvt_pk_bf16_f32 v203, v66, v67
	v_lshl_or_b32 v66, s20, 9, v165
	s_nop 1
	v_permlane16_swap_b32_e32 v200, v202
	v_permlane16_swap_b32_e32 v201, v203
	global_store_dwordx4 v[72:73], v[200:203], off sc1
	v_or_b32_e32 v64, s11, v66
	v_lshlrev_b32_e32 v67, 6, v64
	v_or_b32_e32 v64, v67, v162
	v_ashrrev_i32_e32 v65, 31, v64
	v_pk_mul_f32 v[56:57], v[56:57], v[154:155]
	v_lshl_add_u64 v[64:65], v[64:65], 4, v[136:137]
	v_pk_mul_f32 v[62:63], v[62:63], v[160:161]
	v_cvt_pk_bf16_f32 v188, v60, v61
	v_pk_mul_f32 v[58:59], v[58:59], v[158:159]
	v_cvt_pk_bf16_f32 v189, v62, v63
	v_cvt_pk_bf16_f32 v190, v56, v57
	v_cvt_pk_bf16_f32 v191, v58, v59
	s_nop 1
	v_permlane16_swap_b32_e32 v188, v190
	v_permlane16_swap_b32_e32 v189, v191
	global_store_dwordx4 v[64:65], v[188:191], off sc1
	v_or_b32_e32 v56, s13, v66
	v_lshlrev_b32_e32 v58, 6, v56
	v_or_b32_e32 v56, v58, v162
	v_ashrrev_i32_e32 v57, 31, v56
	v_pk_mul_f32 v[52:53], v[52:53], v[148:149]
	v_pk_mul_f32 v[48:49], v[48:49], v[146:147]
	v_lshl_add_u64 v[56:57], v[56:57], 4, v[136:137]
	v_pk_mul_f32 v[54:55], v[54:55], v[152:153]
	v_cvt_pk_bf16_f32 v192, v52, v53
	v_pk_mul_f32 v[50:51], v[50:51], v[150:151]
	v_cvt_pk_bf16_f32 v193, v54, v55
	v_cvt_pk_bf16_f32 v194, v48, v49
	v_cvt_pk_bf16_f32 v195, v50, v51
	s_nop 1
	v_permlane16_swap_b32_e32 v192, v194
	v_permlane16_swap_b32_e32 v193, v195
	global_store_dwordx4 v[56:57], v[192:195], off sc1
	v_or_b32_e32 v48, v67, v166
	v_ashrrev_i32_e32 v49, 31, v48
	v_pk_mul_f32 v[44:45], v[44:45], v[156:157]
	v_pk_mul_f32 v[40:41], v[40:41], v[154:155]
	v_lshl_add_u64 v[48:49], v[48:49], 4, v[136:137]
	v_pk_mul_f32 v[46:47], v[46:47], v[160:161]
	v_cvt_pk_bf16_f32 v196, v44, v45
	v_pk_mul_f32 v[42:43], v[42:43], v[158:159]
	v_cvt_pk_bf16_f32 v197, v46, v47
	v_cvt_pk_bf16_f32 v198, v40, v41
	v_cvt_pk_bf16_f32 v199, v42, v43
	s_nop 1
	v_permlane16_swap_b32_e32 v196, v198
	v_permlane16_swap_b32_e32 v197, v199
	global_store_dwordx4 v[48:49], v[196:199], off sc1
	v_or_b32_e32 v40, v58, v166
	v_ashrrev_i32_e32 v41, 31, v40
	v_pk_mul_f32 v[36:37], v[36:37], v[148:149]
	v_pk_mul_f32 v[34:35], v[34:35], v[150:151]
	v_pk_mul_f32 v[32:33], v[32:33], v[146:147]
	v_lshl_add_u64 v[40:41], v[40:41], 4, v[136:137]
	v_pk_mul_f32 v[38:39], v[38:39], v[152:153]
	v_cvt_pk_bf16_f32 v200, v36, v37
	v_pk_mul_f32 v[28:29], v[28:29], v[156:157]
	v_cvt_pk_bf16_f32 v201, v38, v39
	v_cvt_pk_bf16_f32 v202, v32, v33
	v_cvt_pk_bf16_f32 v203, v34, v35
	v_or_b32_e32 v34, 2, v66
	s_nop 1
	v_permlane16_swap_b32_e32 v200, v202
	v_permlane16_swap_b32_e32 v201, v203
	global_store_dwordx4 v[40:41], v[200:203], off sc1
	v_or_b32_e32 v32, s11, v34
	v_lshlrev_b32_e32 v35, 6, v32
	v_or_b32_e32 v32, v35, v162
	v_ashrrev_i32_e32 v33, 31, v32
	v_pk_mul_f32 v[24:25], v[24:25], v[154:155]
	v_lshl_add_u64 v[32:33], v[32:33], 4, v[136:137]
	v_pk_mul_f32 v[30:31], v[30:31], v[160:161]
	v_cvt_pk_bf16_f32 v188, v28, v29
	v_pk_mul_f32 v[26:27], v[26:27], v[158:159]
	v_cvt_pk_bf16_f32 v189, v30, v31
	v_cvt_pk_bf16_f32 v190, v24, v25
	v_cvt_pk_bf16_f32 v191, v26, v27
	s_nop 1
	v_permlane16_swap_b32_e32 v188, v190
	v_permlane16_swap_b32_e32 v189, v191
	global_store_dwordx4 v[32:33], v[188:191], off sc1
	v_or_b32_e32 v24, s13, v34
	v_lshlrev_b32_e32 v26, 6, v24
	v_or_b32_e32 v24, v26, v162
	v_ashrrev_i32_e32 v25, 31, v24
	v_pk_mul_f32 v[20:21], v[20:21], v[148:149]
	v_pk_mul_f32 v[16:17], v[16:17], v[146:147]
	v_lshl_add_u64 v[24:25], v[24:25], 4, v[136:137]
	v_pk_mul_f32 v[22:23], v[22:23], v[152:153]
	v_cvt_pk_bf16_f32 v192, v20, v21
	v_pk_mul_f32 v[18:19], v[18:19], v[150:151]
	v_cvt_pk_bf16_f32 v193, v22, v23
	v_cvt_pk_bf16_f32 v194, v16, v17
	v_cvt_pk_bf16_f32 v195, v18, v19
	s_nop 1
	v_permlane16_swap_b32_e32 v192, v194
	v_permlane16_swap_b32_e32 v193, v195
	global_store_dwordx4 v[24:25], v[192:195], off sc1
	v_or_b32_e32 v16, v35, v166
	v_ashrrev_i32_e32 v17, 31, v16
	v_pk_mul_f32 v[12:13], v[12:13], v[156:157]
	v_pk_mul_f32 v[8:9], v[8:9], v[154:155]
	v_lshl_add_u64 v[16:17], v[16:17], 4, v[136:137]
	v_pk_mul_f32 v[14:15], v[14:15], v[160:161]
	v_cvt_pk_bf16_f32 v196, v12, v13
	v_pk_mul_f32 v[10:11], v[10:11], v[158:159]
	v_cvt_pk_bf16_f32 v197, v14, v15
	v_cvt_pk_bf16_f32 v198, v8, v9
	v_cvt_pk_bf16_f32 v199, v10, v11
	s_nop 1
	v_permlane16_swap_b32_e32 v196, v198
	v_permlane16_swap_b32_e32 v197, v199
	global_store_dwordx4 v[16:17], v[196:199], off sc1
	v_or_b32_e32 v8, v26, v166
	v_ashrrev_i32_e32 v9, 31, v8
	v_pk_mul_f32 v[4:5], v[4:5], v[148:149]
	v_pk_mul_f32 v[0:1], v[0:1], v[146:147]
	v_lshl_add_u64 v[8:9], v[8:9], 4, v[136:137]
	v_pk_mul_f32 v[6:7], v[6:7], v[152:153]
	v_pk_mul_f32 v[2:3], v[2:3], v[150:151]
	v_cvt_pk_bf16_f32 v200, v4, v5
	v_cvt_pk_bf16_f32 v201, v6, v7
	v_cvt_pk_bf16_f32 v202, v0, v1
	v_cvt_pk_bf16_f32 v203, v2, v3
	s_nop 1
	v_permlane16_swap_b32_e32 v200, v202
	v_permlane16_swap_b32_e32 v201, v203
	global_store_dwordx4 v[8:9], v[200:203], off sc1
	s_mov_b64 s[20:21], s[14:15]
	s_cbranch_vccz .LBB0_569
	s_waitcnt vmcnt(0)
	s_cmpk_gt_u32 s26, 0xff
	s_cbranch_scc1 .LBB0_580
	s_barrier
